# v019 + grid barrier: non-leader workgroups spin on the cross-XCC release generation (TOPGEN) directly instead of their XCC's XGEN word (one hop less per barrier, 14 barriers); each workgroup still doe
# speedup vs baseline: 1.0020x; 1.0000x over previous
; __device__ __forceinline__ unsigned xb_ld(unsigned* p)              { return __hip_atomic_load(p, __ATOMIC_RELAXED, __HIP_MEMORY_SCOPE_AGENT); }
; __device__ __forceinline__ unsigned xb_add(unsigned* p, unsigned v) { return __hip_atomic_fetch_add(p, v, __ATOMIC_RELAXED, __HIP_MEMORY_SCOPE_AGENT); }
; #define XB_SPIN(cond, bar) do { unsigned _sp = 0; while (cond) { __builtin_amdgcn_s_sleep(1); \
;     if ((++_sp & 255u) == 0u) { if (xb_ld(&(bar)[XB_TMO])) break; if (_sp > XB_SPIN_CAP) { atomicAdd(&(bar)[XB_TMO], 1u); break; } } } } while (0)
; __device__ __forceinline__ void xcd_barrier(const XcdBarrier& b) {
;     ...
;         const unsigned old = xb_add(&bar[XB_XSUB(b.x)], 1u);
;         const unsigned gen = old / nloc;
;         if (old + 1u == (gen + 1u) * nloc) {
;             __builtin_amdgcn_fence(__ATOMIC_RELEASE, "agent");
;             asm volatile("s_waitcnt vmcnt(0)" ::: "memory");
;             const unsigned og = xb_add(&bar[XB_TOP], 1u);
;             const unsigned tg = og / nx;
;             if (og + 1u == (tg + 1u) * nx) xb_add(&bar[XB_TOPGEN], 1u);
;             else XB_SPIN(xb_ld(&bar[XB_TOPGEN]) == tg, bar);
;             __builtin_amdgcn_fence(__ATOMIC_ACQUIRE, "agent");
;             xb_add(&bar[XB_XGEN(b.x)], 1u);
;             asm volatile("s_waitcnt vmcnt(0)" ::: "memory");
;         } else {
;             XB_SPIN(xb_ld(&bar[XB_XGEN(b.x)]) == gen, bar);
.LBB0_170:
	s_or_b64 exec, exec, s[8:9]
	v_cvt_f32_u32_e32 v4, v2
	s_waitcnt vmcnt(0)
	v_readfirstlane_b32 s6, v3
	v_sub_u32_e32 v3, 0, v2
	v_rcp_iflag_f32_e32 v4, v4
	v_add_u32_e32 v5, s6, v1
	v_mul_f32_e32 v4, 0x4f7ffffe, v4
	v_cvt_u32_f32_e32 v4, v4
	v_mul_lo_u32 v1, v3, v4
	v_mul_hi_u32 v1, v4, v1
	v_add_u32_e32 v1, v4, v1
	v_mul_hi_u32 v1, v5, v1
	v_mul_lo_u32 v3, v1, v2
	v_sub_u32_e32 v3, v5, v3
	v_add_u32_e32 v4, 1, v1
	v_cmp_ge_u32_e32 vcc, v3, v2
	s_nop 1
	v_cndmask_b32_e32 v1, v1, v4, vcc
	v_sub_u32_e32 v4, v3, v2
	v_cndmask_b32_e32 v3, v3, v4, vcc
	v_add_u32_e32 v4, 1, v1
	v_cmp_ge_u32_e32 vcc, v3, v2
	v_add_u32_e32 v3, 1, v5
	s_nop 0
	v_cndmask_b32_e32 v1, v1, v4, vcc
	v_mul_lo_u32 v4, v2, v1
	v_add_u32_e32 v2, v4, v2
	v_cmp_ne_u32_e32 vcc, v3, v2
	s_and_saveexec_b64 s[6:7], vcc
	s_xor_b64 s[6:7], exec, s[6:7]
	s_cbranch_execz .LBB0_184
	s_waitcnt lgkmcnt(0)
	s_add_u32 s12, s82, 0x3c3500
	s_addc_u32 s13, s83, 0
	v_mov_b32_e32 v0, 0
	global_load_dword v0, v0, s[12:13] sc1
	s_waitcnt vmcnt(0)
	v_cmp_eq_u32_e32 vcc, v0, v1
	s_and_saveexec_b64 s[8:9], vcc
	s_cbranch_execz .LBB0_183
	s_add_u32 s10, s82, 0x3c0200
	s_addc_u32 s11, s83, 0
	s_mov_b32 s24, 1
	s_mov_b64 s[14:15], 0
	v_mov_b32_e32 v0, 0
	s_branch .LBB0_174

; __device__ __forceinline__ unsigned xb_ld(unsigned* p)              { return __hip_atomic_load(p, __ATOMIC_RELAXED, __HIP_MEMORY_SCOPE_AGENT); }
; __device__ __forceinline__ unsigned xb_add(unsigned* p, unsigned v) { return __hip_atomic_fetch_add(p, v, __ATOMIC_RELAXED, __HIP_MEMORY_SCOPE_AGENT); }
; #define XB_SPIN(cond, bar) do { unsigned _sp = 0; while (cond) { __builtin_amdgcn_s_sleep(1); \
;     if ((++_sp & 255u) == 0u) { if (xb_ld(&(bar)[XB_TMO])) break; if (_sp > XB_SPIN_CAP) { atomicAdd(&(bar)[XB_TMO], 1u); break; } } } } while (0)
; __device__ __forceinline__ void xcd_barrier(const XcdBarrier& b) {
;     ...
;         const unsigned old = xb_add(&bar[XB_XSUB(b.x)], 1u);
;         const unsigned gen = old / nloc;
;         if (old + 1u == (gen + 1u) * nloc) {
;             __builtin_amdgcn_fence(__ATOMIC_RELEASE, "agent");
;             asm volatile("s_waitcnt vmcnt(0)" ::: "memory");
;             const unsigned og = xb_add(&bar[XB_TOP], 1u);
;             const unsigned tg = og / nx;
;             if (og + 1u == (tg + 1u) * nx) xb_add(&bar[XB_TOPGEN], 1u);
;             else XB_SPIN(xb_ld(&bar[XB_TOPGEN]) == tg, bar);
;             __builtin_amdgcn_fence(__ATOMIC_ACQUIRE, "agent");
;             xb_add(&bar[XB_XGEN(b.x)], 1u);
;             asm volatile("s_waitcnt vmcnt(0)" ::: "memory");
;         } else {
;             XB_SPIN(xb_ld(&bar[XB_XGEN(b.x)]) == gen, bar);
.LBB0_698:
	s_or_b64 exec, exec, s[8:9]
	v_cvt_f32_u32_e32 v4, v2
	s_waitcnt vmcnt(0)
	v_readfirstlane_b32 s6, v3
	v_sub_u32_e32 v3, 0, v2
	v_rcp_iflag_f32_e32 v4, v4
	v_add_u32_e32 v5, s6, v1
	v_mul_f32_e32 v4, 0x4f7ffffe, v4
	v_cvt_u32_f32_e32 v4, v4
	v_mul_lo_u32 v1, v3, v4
	v_mul_hi_u32 v1, v4, v1
	v_add_u32_e32 v1, v4, v1
	v_mul_hi_u32 v1, v5, v1
	v_mul_lo_u32 v3, v1, v2
	v_sub_u32_e32 v3, v5, v3
	v_add_u32_e32 v4, 1, v1
	v_cmp_ge_u32_e32 vcc, v3, v2
	s_nop 1
	v_cndmask_b32_e32 v1, v1, v4, vcc
	v_sub_u32_e32 v4, v3, v2
	v_cndmask_b32_e32 v3, v3, v4, vcc
	v_add_u32_e32 v4, 1, v1
	v_cmp_ge_u32_e32 vcc, v3, v2
	v_add_u32_e32 v3, 1, v5
	s_nop 0
	v_cndmask_b32_e32 v1, v1, v4, vcc
	v_mul_lo_u32 v4, v2, v1
	v_add_u32_e32 v2, v4, v2
	v_cmp_ne_u32_e32 vcc, v3, v2
	s_and_saveexec_b64 s[6:7], vcc
	s_xor_b64 s[6:7], exec, s[6:7]
	s_cbranch_execz .LBB0_712
	s_waitcnt lgkmcnt(0)
	s_add_u32 s14, s82, 0x3c3500
	s_addc_u32 s15, s83, 0
	v_mov_b32_e32 v0, 0
	global_load_dword v0, v0, s[14:15] sc1
	s_waitcnt vmcnt(0)
	v_cmp_eq_u32_e32 vcc, v0, v1
	s_and_saveexec_b64 s[8:9], vcc
	s_cbranch_execz .LBB0_711
	s_add_u32 s12, s82, 0x3c0200
	s_addc_u32 s13, s83, 0
	s_mov_b32 s24, 1
	s_mov_b64 s[16:17], 0
	v_mov_b32_e32 v0, 0
	s_branch .LBB0_702
